# phase 0 transpose engine: three items of weight-tile loads in flight instead of two (deeper counted-vmcnt ring)
# baseline (speedup 1.0000x reference)
.LBB0_57:
.LBB0_60:
.LBB0_63:
.LBB0_66:
	s_andn2_b64 vcc, exec, s[6:7]
	s_cbranch_vccnz .LBB0_72
	v_mov_b32_e32 v40, v188
	v_lshrrev_b32_e32 v41, 4, v40
	v_and_b32_e32 v43, 15, v40
	v_lshlrev_b32_e32 v42, 4, v43
	v_lshlrev_b32_e32 v43, 2, v43
	v_lshrrev_b32_e32 v44, 3, v40
	v_and_b32_e32 v45, 7, v40
	v_lshlrev_b32_e32 v45, 4, v45
	v_mov_b32_e32 v95, 0
	s_cmp_eq_u32 s98, 0
	s_cbranch_scc0 .Ltr_steady
	s_mov_b32 s30, s39
	s_mov_b32 s49, 0
	s_mov_b32 s91, 4
	s_branch .Ltr_fill
.Ltr_steady:
	s_mul_i32 s30, s78, 3
	s_add_i32 s30, s39, s30
	s_add_i32 s49, s99, 3
	s_cmp_ge_u32 s49, 4
	s_cbranch_scc0 .Ltr_slotok
	s_sub_i32 s49, s49, 4

.Ltr_ld2:
	s_cmp_eq_u32 s49, 2
	s_cbranch_scc0 .Ltr_ld3
	global_load_dwordx4 v[76:79], v46, s[10:11] nt
	global_load_dwordx4 v[80:83], v46, s[88:89] nt
	v_mov_b32_e32 v88, v92
	v_mov_b32_e32 v89, v93
	s_branch .Ltr_ldone
.Ltr_ld3:
	global_load_dwordx4 v[122:125], v46, s[10:11] nt
	global_load_dwordx4 v[126:129], v46, s[88:89] nt
	v_mov_b32_e32 v130, v92
	v_mov_b32_e32 v131, v93

.Ltr_nomask:
	v_cmp_gt_u32_e64 s[10:11], s6, v43
	s_cmp_eq_u32 s98, 0
	s_cbranch_scc0 .Ltr_wt1
	s_waitcnt vmcnt(6)
	s_branch .Ltr_wdone
.Ltr_wt1:
	s_cmp_eq_u32 s98, 1
	s_cbranch_scc0 .Ltr_wt2
	s_waitcnt vmcnt(7)
	s_branch .Ltr_wdone
.Ltr_wt2:
	s_cmp_eq_u32 s98, 2
	s_cbranch_scc0 .Ltr_wt3
	s_waitcnt vmcnt(8)
	s_branch .Ltr_wdone
.Ltr_wt3:
	s_waitcnt vmcnt(9)

.Ltr_mv2:
	s_cmp_eq_u32 s99, 2
	s_cbranch_scc0 .Ltr_mv3
	v_mul_f32_e32 v96, s7, v76
	v_mul_f32_e32 v97, s7, v77
	v_mul_f32_e32 v98, s7, v78
	v_mul_f32_e32 v99, s7, v79
	v_mul_f32_e32 v100, s7, v80
	v_mul_f32_e32 v101, s7, v81
	v_mul_f32_e32 v102, s7, v82
	v_mul_f32_e32 v103, s7, v83
	v_mov_b32_e32 v104, v88
	v_mov_b32_e32 v105, v89
	s_branch .Ltr_mvdone
.Ltr_mv3:
	v_mul_f32_e32 v96, s7, v122
	v_mul_f32_e32 v97, s7, v123
	v_mul_f32_e32 v98, s7, v124
	v_mul_f32_e32 v99, s7, v125
	v_mul_f32_e32 v100, s7, v126
	v_mul_f32_e32 v101, s7, v127
	v_mul_f32_e32 v102, s7, v128
	v_mul_f32_e32 v103, s7, v129
	v_mov_b32_e32 v104, v130
	v_mov_b32_e32 v105, v131
.Ltr_mvdone:
	v_cndmask_b32_e64 v96, 0, v96, s[10:11]
	v_cndmask_b32_e64 v97, 0, v97, s[10:11]
	v_cndmask_b32_e64 v98, 0, v98, s[10:11]
	v_cndmask_b32_e64 v99, 0, v99, s[10:11]
	v_cndmask_b32_e64 v100, 0, v100, s[10:11]
	v_cndmask_b32_e64 v101, 0, v101, s[10:11]
	v_cndmask_b32_e64 v102, 0, v102, s[10:11]
	v_cndmask_b32_e64 v103, 0, v103, s[10:11]
	v_mul_u32_u24_e32 v106, 0x110, v41
	v_add3_u32 v106, v106, v42, s101
	ds_write_b128 v106, v[96:99]
	ds_write_b128 v106, v[100:103] offset:8704
	v_lshlrev_b32_e32 v47, 3, v40
	v_and_b32_e32 v47, 56, v47
	v_mul_u32_u24_e32 v107, 0x110, v47
	v_lshlrev_b32_e32 v48, 2, v44
	v_add3_u32 v107, v107, v48, s101
	v_add_u32_e32 v108, 0x400, v107
	s_waitcnt lgkmcnt(0)
	s_barrier
	ds_read2_b32 v[110:111], v107 offset1:68
	ds_read2_b32 v[112:113], v107 offset0:136 offset1:204
	ds_read2_b32 v[114:115], v108 offset0:16 offset1:84
	ds_read2_b32 v[116:117], v108 offset0:152 offset1:220
	s_xor_b32 s101, s101, 0x4400
	s_add_i32 s99, s99, 1
	s_cmp_ge_u32 s99, 4
	s_cselect_b32 s99, 0, s99
	s_min_u32 s98, s98, 2
	s_add_i32 s98, s98, 1
	s_waitcnt lgkmcnt(3)
	v_cvt_pk_bf16_f32 v118, v110, v111
	s_waitcnt lgkmcnt(2)
	v_cvt_pk_bf16_f32 v119, v112, v113
	s_waitcnt lgkmcnt(1)
	v_cvt_pk_bf16_f32 v120, v114, v115
	s_waitcnt lgkmcnt(0)
	v_cvt_pk_bf16_f32 v121, v116, v117
	global_store_dwordx4 v[104:105], v[118:121], off
